# retention units: all four K/V tiles staged into four LDS buffers up front; tile loop has no global loads, LDS writes or barriers
# baseline (speedup 1.0000x reference)
.LBB0_1183:
	s_waitcnt vmcnt(1)
	v_mul_f32_e32 v0, 0xbfb8aa3b, v2
	v_rndne_f32_e32 v3, v0
	s_mov_b32 s12, 0xbfb8aa3b
	v_sub_f32_e32 v4, v0, v3
	v_fma_f32 v0, v2, s12, -v0
	v_fmac_f32_e32 v0, 0xb2a5705f, v2
	v_add_f32_e32 v0, v4, v0
	v_exp_f32_e32 v0, v0
	v_cvt_i32_f32_e32 v3, v3
	s_mov_b32 s14, 0x42ce8ed0
	v_cmp_nlt_f32_e32 vcc, s14, v2
	s_mov_b32 s24, 0xc2b17218
	v_ldexp_f32 v3, v0, v3
	v_cndmask_b32_e32 v3, 0, v3, vcc
	v_cmp_ngt_f32_e32 vcc, s24, v2
	s_mov_b32 s13, 0x3f2aaaab
	s_mov_b32 s15, 0x3f317218
	v_cndmask_b32_e32 v4, v172, v3, vcc
	v_add_f32_e32 v5, 1.0, v4
	v_add_f32_e32 v2, -1.0, v5
	v_sub_f32_e32 v3, v2, v5
	v_add_f32_e32 v3, 1.0, v3
	v_sub_f32_e32 v2, v4, v2
	v_add_f32_e32 v6, v2, v3
	v_frexp_mant_f32_e32 v7, v5
	v_cvt_f64_f32_e32 v[2:3], v5
	v_frexp_exp_i32_f64_e32 v2, v[2:3]
	v_cmp_gt_f32_e32 vcc, s13, v7
	s_mov_b32 s21, 0x7f800000
	s_mov_b32 s25, 0x33800000
	v_subbrev_co_u32_e32 v2, vcc, 0, v2, vcc
	v_sub_u32_e32 v3, 0, v2
	v_ldexp_f32 v5, v5, v3
	v_ldexp_f32 v3, v6, v3
	v_add_f32_e32 v6, -1.0, v5
	v_add_f32_e32 v9, 1.0, v5
	v_add_f32_e32 v7, 1.0, v6
	v_add_f32_e32 v10, -1.0, v9
	v_sub_f32_e32 v7, v5, v7
	v_sub_f32_e32 v5, v5, v10
	v_add_f32_e32 v7, v3, v7
	v_add_f32_e32 v3, v3, v5
	v_add_f32_e32 v5, v9, v3
	v_rcp_f32_e32 v10, v5
	v_add_f32_e32 v8, v6, v7
	v_sub_f32_e32 v6, v6, v8
	v_add_f32_e32 v6, v7, v6
	v_sub_f32_e32 v7, v9, v5
	v_add_f32_e32 v3, v3, v7
	v_mul_f32_e32 v7, v8, v10
	v_mul_f32_e32 v9, v5, v7
	v_fma_f32 v11, v7, v5, -v9
	v_fmac_f32_e32 v11, v7, v3
	v_add_f32_e32 v12, v9, v11
	v_sub_f32_e32 v13, v8, v12
	v_sub_f32_e32 v8, v8, v13
	v_sub_f32_e32 v9, v12, v9
	v_sub_f32_e32 v8, v8, v12
	v_add_f32_e32 v6, v6, v8
	v_sub_f32_e32 v8, v9, v11
	v_add_f32_e32 v6, v8, v6
	v_add_f32_e32 v8, v13, v6
	v_mul_f32_e32 v9, v10, v8
	v_mul_f32_e32 v11, v5, v9
	v_fma_f32 v5, v9, v5, -v11
	v_fmac_f32_e32 v5, v9, v3
	v_sub_f32_e32 v3, v13, v8
	v_add_f32_e32 v3, v6, v3
	v_add_f32_e32 v6, v11, v5
	v_sub_f32_e32 v12, v8, v6
	v_sub_f32_e32 v8, v8, v12
	v_sub_f32_e32 v11, v6, v11
	v_sub_f32_e32 v6, v8, v6
	v_add_f32_e32 v3, v3, v6
	v_sub_f32_e32 v5, v11, v5
	v_cvt_f32_i32_e32 v2, v2
	v_add_f32_e32 v3, v5, v3
	v_add_f32_e32 v5, v7, v9
	v_add_f32_e32 v3, v12, v3
	v_sub_f32_e32 v6, v5, v7
	v_mul_f32_e32 v3, v10, v3
	v_sub_f32_e32 v6, v9, v6
	v_add_f32_e32 v3, v6, v3
	v_mul_f32_e32 v9, 0x3f317218, v2
	v_add_f32_e32 v6, v5, v3
	v_fma_f32 v10, v2, s15, -v9
	v_mul_f32_e32 v7, v6, v6
	v_fmac_f32_e32 v10, 0xb102e308, v2
	v_sub_f32_e32 v2, v6, v5
	v_fmamk_f32 v8, v7, 0x3e9b6dac, v168
	v_sub_f32_e32 v2, v3, v2
	v_add_f32_e32 v3, v9, v10
	v_fmaak_f32 v8, v7, v8, 0x3f2aaada
	v_sub_f32_e32 v5, v3, v9
	v_ldexp_f32 v9, v6, 1
	v_mul_f32_e32 v6, v6, v7
	v_mul_f32_e32 v6, v6, v8
	v_add_f32_e32 v7, v9, v6
	v_sub_f32_e32 v8, v7, v9
	v_ldexp_f32 v2, v2, 1
	v_sub_f32_e32 v6, v6, v8
	v_add_f32_e32 v2, v2, v6
	v_add_f32_e32 v6, v7, v2
	v_sub_f32_e32 v7, v6, v7
	v_sub_f32_e32 v2, v2, v7
	v_add_f32_e32 v7, v3, v6
	v_sub_f32_e32 v8, v7, v3
	v_sub_f32_e32 v9, v7, v8
	v_sub_f32_e32 v5, v10, v5
	v_sub_f32_e32 v3, v3, v9
	v_sub_f32_e32 v6, v6, v8
	v_add_f32_e32 v3, v6, v3
	v_add_f32_e32 v6, v5, v2
	v_sub_f32_e32 v8, v6, v5
	v_sub_f32_e32 v9, v6, v8
	v_sub_f32_e32 v5, v5, v9
	v_sub_f32_e32 v2, v2, v8
	v_add_f32_e32 v3, v6, v3
	v_add_f32_e32 v2, v2, v5
	v_add_f32_e32 v5, v7, v3
	v_sub_f32_e32 v6, v5, v7
	v_sub_f32_e32 v3, v3, v6
	v_add_f32_e32 v2, v2, v3
	s_waitcnt vmcnt(0)
	v_mul_f32_e32 v3, 0xbfb8aa3b, v1
	v_add_f32_e32 v2, v5, v2
	v_rndne_f32_e32 v5, v3
	v_sub_f32_e32 v6, v3, v5
	v_fma_f32 v3, v1, s12, -v3
	v_fmac_f32_e32 v3, 0xb2a5705f, v1
	v_add_f32_e32 v3, v6, v3
	v_exp_f32_e32 v3, v3
	v_cvt_i32_f32_e32 v5, v5
	v_cmp_neq_f32_e32 vcc, s21, v4
	s_lshl_b32 s26, s1, 8
	s_mul_i32 s1, s1, 0x160000
	v_cndmask_b32_e32 v2, v172, v2, vcc
	v_cmp_lt_f32_e64 vcc, |v4|, s25
	v_readlane_b32 s8, v254, 62
	s_mul_hi_u32 s0, s26, 0x1600
	v_cndmask_b32_e32 v2, v2, v4, vcc
	v_mul_f32_e32 v115, 0xbfb8aa3b, v2
	v_ldexp_f32 v2, v3, v5
	v_cmp_nlt_f32_e32 vcc, s14, v1
	v_readlane_b32 s9, v254, 63
	s_add_u32 s7, s8, s1
	v_cndmask_b32_e32 v2, 0, v2, vcc
	v_cmp_ngt_f32_e32 vcc, s24, v1
	s_addc_u32 s8, s9, s0
	s_lshl_b32 s19, s6, 6
	v_cndmask_b32_e32 v1, v172, v2, vcc
	v_add_f32_e32 v4, 1.0, v1
	v_add_f32_e32 v2, -1.0, v4
	v_sub_f32_e32 v3, v2, v4
	v_add_f32_e32 v3, 1.0, v3
	v_sub_f32_e32 v2, v1, v2
	v_add_f32_e32 v5, v2, v3
	v_frexp_mant_f32_e32 v6, v4
	v_cvt_f64_f32_e32 v[2:3], v4
	v_frexp_exp_i32_f64_e32 v2, v[2:3]
	v_cmp_gt_f32_e32 vcc, s13, v6
	s_lshl_b32 s3, s6, 7
	s_add_u32 s16, s7, s3
	v_subbrev_co_u32_e32 v10, vcc, 0, v2, vcc
	v_sub_u32_e32 v2, 0, v10
	v_ldexp_f32 v3, v4, v2
	v_add_f32_e32 v4, -1.0, v3
	v_add_f32_e32 v7, 1.0, v3
	v_ldexp_f32 v2, v5, v2
	v_add_f32_e32 v5, 1.0, v4
	v_add_f32_e32 v8, -1.0, v7
	v_sub_f32_e32 v5, v3, v5
	v_sub_f32_e32 v3, v3, v8
	v_add_f32_e32 v5, v2, v5
	v_add_f32_e32 v2, v2, v3
	v_add_f32_e32 v11, v7, v2
	v_rcp_f32_e32 v12, v11
	v_add_f32_e32 v6, v4, v5
	v_sub_f32_e32 v4, v4, v6
	v_add_f32_e32 v3, v5, v4
	v_sub_f32_e32 v4, v7, v11
	v_mul_f32_e32 v14, v6, v12
	v_add_f32_e32 v13, v2, v4
	v_mul_f32_e32 v2, v11, v14
	v_fma_f32 v4, v14, v11, -v2
	v_fmac_f32_e32 v4, v14, v13
	s_addc_u32 s17, s8, 0
	s_mul_i32 s6, s6, 0x500000
	v_readlane_b32 s8, v255, 33
	v_add_f32_e32 v5, v2, v4
	s_add_u32 s10, s8, s6
	v_readlane_b32 s8, v255, 34
	v_sub_f32_e32 v15, v6, v5
	s_addc_u32 s11, s8, 0
	s_lshl_b64 s[8:9], s[26:27], 1
	v_sub_f32_e32 v6, v6, v15
	v_mov_b32_e32 v19, v128
	s_add_u32 s10, s10, s8
	v_sub_f32_e32 v2, v5, v2
	v_sub_f32_e32 v5, v6, v5
	s_addc_u32 s11, s11, s9
	v_readfirstlane_b32 s12, v19
	v_add_f32_e32 v3, v3, v5
	v_sub_f32_e32 v2, v2, v4
	s_ashr_i32 s12, s12, 1
	v_add_f32_e32 v16, v2, v3
	v_mov_b32_e32 v2, s12
	s_movk_i32 s12, 0xffe0
	v_lshlrev_b32_e32 v22, 3, v19
	v_bfe_u32 v20, v19, 5, 1
	v_bfi_b32 v116, s12, v2, v19
	v_mov_b64_e32 v[2:3], s[16:17]
	s_movk_i32 s14, 0x1600
	v_ashrrev_i32_e32 v21, 3, v19
	v_and_b32_e32 v23, 56, v22
	v_mad_i64_i32 v[112:113], s[12:13], v116, s14, v[2:3]
	v_lshlrev_b32_e32 v130, 4, v20
	v_mad_i64_i32 v[2:3], s[12:13], v21, s14, v[2:3]
	v_lshlrev_b32_e32 v6, 1, v23
	v_mov_b32_e32 v7, v131
	v_lshl_add_u64 v[4:5], v[112:113], 0, v[130:131]
	v_lshl_add_u64 v[2:3], v[2:3], 0, v[6:7]
	v_mov_b64_e32 v[8:9], s[10:11]
	s_mov_b32 s12, 0x14000
	global_load_dwordx4 v[108:111], v[4:5], off
	global_load_dwordx4 v[104:107], v[4:5], off offset:32
	global_load_dwordx4 v[100:103], v[4:5], off offset:64
	global_load_dwordx4 v[96:99], v[4:5], off offset:96
	s_barrier
	global_load_dwordx4 v[2:5], v[2:3], off offset:1024
	v_mad_i64_i32 v[8:9], s[10:11], v21, s12, v[8:9]
	v_lshl_add_u64 v[6:7], v[8:9], 0, v[6:7]
	global_load_dwordx4 v[6:9], v[6:7], off
	v_add_f32_e32 v17, v15, v16
	v_mul_f32_e32 v18, v12, v17
	v_mul_f32_e32 v24, v11, v18
	v_fma_f32 v11, v18, v11, -v24
	v_fmac_f32_e32 v11, v18, v13
	v_sub_f32_e32 v13, v15, v17
	v_add_f32_e32 v15, v24, v11
	v_add_f32_e32 v13, v16, v13
	v_sub_f32_e32 v16, v15, v24
	v_sub_f32_e32 v24, v17, v15
	v_sub_f32_e32 v17, v17, v24
	v_sub_f32_e32 v15, v17, v15
	v_add_f32_e32 v13, v13, v15
	v_sub_f32_e32 v11, v16, v11
	v_add_f32_e32 v11, v11, v13
	v_add_f32_e32 v11, v24, v11
	v_cvt_f32_i32_e32 v10, v10
	v_mul_f32_e32 v11, v12, v11
	v_add_f32_e32 v12, v14, v18
	v_sub_f32_e32 v13, v12, v14
	v_sub_f32_e32 v13, v18, v13
	v_add_f32_e32 v11, v13, v11
	v_mul_f32_e32 v16, 0x3f317218, v10
	v_add_f32_e32 v13, v12, v11
	v_fma_f32 v17, v10, s15, -v16
	v_mul_f32_e32 v14, v13, v13
	v_fmac_f32_e32 v17, 0xb102e308, v10
	v_sub_f32_e32 v10, v13, v12
	v_fmamk_f32 v15, v14, 0x3e9b6dac, v168
	v_sub_f32_e32 v10, v11, v10
	v_add_f32_e32 v11, v16, v17
	v_fmaak_f32 v15, v14, v15, 0x3f2aaada
	v_sub_f32_e32 v12, v11, v16
	v_ldexp_f32 v16, v13, 1
	v_mul_f32_e32 v13, v13, v14
	v_mul_f32_e32 v13, v13, v15
	v_add_f32_e32 v14, v16, v13
	v_sub_f32_e32 v15, v14, v16
	v_ldexp_f32 v10, v10, 1
	v_sub_f32_e32 v13, v13, v15
	v_add_f32_e32 v10, v10, v13
	v_add_f32_e32 v13, v14, v10
	v_sub_f32_e32 v14, v13, v14
	v_sub_f32_e32 v10, v10, v14
	v_add_f32_e32 v14, v11, v13
	v_sub_f32_e32 v15, v14, v11
	v_sub_f32_e32 v16, v14, v15
	v_sub_f32_e32 v12, v17, v12
	v_sub_f32_e32 v11, v11, v16
	v_sub_f32_e32 v13, v13, v15
	v_add_f32_e32 v11, v13, v11
	v_add_f32_e32 v13, v12, v10
	v_sub_f32_e32 v15, v13, v12
	v_sub_f32_e32 v16, v13, v15
	v_sub_f32_e32 v12, v12, v16
	v_sub_f32_e32 v10, v10, v15
	v_add_f32_e32 v11, v13, v11
	v_add_f32_e32 v10, v10, v12
	v_add_f32_e32 v12, v14, v11
	v_sub_f32_e32 v13, v12, v14
	v_sub_f32_e32 v11, v11, v13
	v_add_f32_e32 v10, v10, v11
	v_add_f32_e32 v10, v12, v10
	v_cmp_neq_f32_e32 vcc, s21, v1
	s_movk_i32 s10, 0x48
	s_mov_b32 s7, s27
	v_cndmask_b32_e32 v10, v172, v10, vcc
	v_cmp_lt_f32_e64 vcc, |v1|, s25
	v_and_b32_e32 v73, 31, v19
	v_lshlrev_b32_e32 v72, 3, v20
	v_cndmask_b32_e32 v1, v10, v1, vcc
	v_mul_f32_e32 v117, 0xbfb8aa3b, v1
	v_mul_lo_u32 v1, v21, s10
	v_and_b32_e32 v10, 48, v22
	v_add_lshl_u32 v79, v1, v23, 1
	v_add_u32_e32 v1, v1, v10
	v_lshlrev_b32_e32 v10, 2, v19
	v_and_or_b32 v1, v10, 4, v1
	v_lshlrev_b32_e32 v80, 1, v1
	v_add_u32_e32 v1, 0, v79
	s_waitcnt vmcnt(1)
	ds_write_b128 v1, v[2:5]
	v_add_u32_e32 v1, 0, v80
	v_add_u32_e32 v1, 0x2000, v1
	v_mov_b64_e32 v[2:3], s[6:7]
	s_waitcnt vmcnt(0)
	ds_write2_b64 v1, v[6:7], v[8:9] offset0:128 offset1:130
	v_mul_u32_u24_e32 v1, 0x48, v73
	v_mad_i64_i32 v[2:3], s[6:7], v21, s12, v[2:3]
	v_add_lshl_u32 v81, v72, v1, 1
	v_lshlrev_b32_e32 v1, 4, v19
	v_readlane_b32 s6, v253, 8
	v_and_b32_e32 v1, 0x70, v1
	s_add_u32 s6, s6, s8
	v_readlane_b32 s7, v253, 9
	v_or_b32_e32 v2, v2, v1
	s_addc_u32 s7, s7, s9
	s_or_b32 s1, s1, s3
	v_lshl_add_u64 v[74:75], s[6:7], 0, v[2:3]
	v_mov_b32_e32 v2, s1
	v_mov_b32_e32 v3, s0
	v_mad_i64_i32 v[2:3], s[0:1], v21, s14, v[2:3]
	v_readlane_b32 s0, v253, 10
	v_mov_b32_e32 v0, 0
	v_lshlrev_b32_e32 v114, 2, v20
	v_or_b32_e32 v2, v2, v1
	v_readlane_b32 s1, v253, 11
	s_mov_b32 s20, 0
	v_mul_u32_u24_e32 v78, 0x90, v73
	v_sub_u32_e32 v82, v116, v114
	v_lshl_add_u64 v[76:77], s[0:1], 0, v[2:3]
	s_mov_b32 s6, 0
	v_mov_b32_e32 v1, v0
	v_mov_b32_e32 v2, v0
	v_mov_b32_e32 v3, v0
	v_mov_b32_e32 v4, v0
	v_mov_b32_e32 v5, v0
	v_mov_b32_e32 v6, v0
	v_mov_b32_e32 v7, v0
	v_mov_b32_e32 v8, v0
	v_mov_b32_e32 v9, v0
	v_mov_b32_e32 v10, v0
	v_mov_b32_e32 v11, v0
	v_mov_b32_e32 v12, v0
	v_mov_b32_e32 v13, v0
	v_mov_b32_e32 v14, v0
	v_mov_b32_e32 v15, v0
	v_mov_b32_e32 v16, v0
	v_mov_b32_e32 v17, v0
	v_mov_b32_e32 v18, v0
	v_mov_b32_e32 v19, v0
	v_mov_b32_e32 v20, v0
	v_mov_b32_e32 v21, v0
	v_mov_b32_e32 v22, v0
	v_mov_b32_e32 v23, v0
	v_mov_b32_e32 v24, v0
	v_mov_b32_e32 v25, v0
	v_mov_b32_e32 v26, v0
	v_mov_b32_e32 v27, v0
	v_mov_b32_e32 v28, v0
	v_mov_b32_e32 v29, v0
	v_mov_b32_e32 v30, v0
	v_mov_b32_e32 v31, v0
	s_mov_b64 s[8:9], 0x58000
	global_load_dwordx4 v[224:227], v[76:77], off
	global_load_dwordx4 v[228:231], v[74:75], off
	v_lshl_add_u64 v[76:77], v[76:77], 0, s[8:9]
	v_lshl_add_u64 v[74:75], v[74:75], 0, s[30:31]
	global_load_dwordx4 v[232:235], v[76:77], off
	global_load_dwordx4 v[236:239], v[74:75], off
	v_lshl_add_u64 v[76:77], v[76:77], 0, s[8:9]
	v_lshl_add_u64 v[74:75], v[74:75], 0, s[30:31]
	global_load_dwordx4 v[240:243], v[76:77], off
	global_load_dwordx4 v[244:247], v[74:75], off
	v_mul_f32_e32 v214, 0x42600000, v115
	v_mul_f32_e32 v215, 0x42400000, v115
	v_mul_f32_e32 v216, 0x42200000, v115
	v_mul_f32_e32 v217, 0x42000000, v115
	v_exp_f32_e32 v214, v214
	v_exp_f32_e32 v215, v215
	v_exp_f32_e32 v216, v216
	v_exp_f32_e32 v217, v217
	s_nop 0
	v_readfirstlane_b32 s70, v214
	v_readfirstlane_b32 s71, v215
	v_readfirstlane_b32 s72, v216
	v_readfirstlane_b32 s73, v217
	v_mul_f32_e32 v214, 0x41c00000, v115
	v_mul_f32_e32 v215, 0x41800000, v115
	v_mul_f32_e32 v216, 0x41000000, v115
	v_mul_f32_e32 v217, 0x00000000, v115
	v_exp_f32_e32 v214, v214
	v_exp_f32_e32 v215, v215
	v_exp_f32_e32 v216, v216
	v_exp_f32_e32 v217, v217
	s_nop 0
	v_readfirstlane_b32 s74, v214
	v_readfirstlane_b32 s75, v215
	v_readfirstlane_b32 s76, v216
	v_readfirstlane_b32 s77, v217
	v_mul_f32_e32 v214, 0x40400000, v115
	v_mul_f32_e32 v215, 0x40000000, v115
	v_mul_f32_e32 v216, 0x3f800000, v115
	v_mul_f32_e32 v217, 0x00000000, v115
	v_exp_f32_e32 v214, v214
	v_exp_f32_e32 v215, v215
	v_exp_f32_e32 v216, v216
	v_exp_f32_e32 v217, v217
	s_nop 0
	v_readfirstlane_b32 s78, v214
	v_readfirstlane_b32 s79, v215
	v_readfirstlane_b32 s80, v216
	v_readfirstlane_b32 s81, v217
	v_mul_f32_e32 v214, 0x00000000, v117
	v_mul_f32_e32 v215, 0x41000000, v117
	v_mul_f32_e32 v216, 0x41800000, v117
	v_mul_f32_e32 v217, 0x41c00000, v117
	v_exp_f32_e32 v214, v214
	v_exp_f32_e32 v215, v215
	v_exp_f32_e32 v216, v216
	v_exp_f32_e32 v217, v217
	s_nop 0
	v_readfirstlane_b32 s82, v214
	v_readfirstlane_b32 s83, v215
	v_readfirstlane_b32 s84, v216
	v_readfirstlane_b32 s85, v217
	v_mul_f32_e32 v214, 0x42000000, v117
	v_mul_f32_e32 v215, 0x42200000, v117
	v_mul_f32_e32 v216, 0x42400000, v117
	v_mul_f32_e32 v217, 0x42600000, v117
	v_exp_f32_e32 v214, v214
	v_exp_f32_e32 v215, v215
	v_exp_f32_e32 v216, v216
	v_exp_f32_e32 v217, v217
	s_nop 0
	v_readfirstlane_b32 s86, v214
	v_readfirstlane_b32 s87, v215
	v_readfirstlane_b32 s88, v216
	v_readfirstlane_b32 s89, v217
	v_mul_f32_e32 v214, 0x00000000, v117
	v_mul_f32_e32 v215, 0x3f800000, v117
	v_mul_f32_e32 v216, 0x40000000, v117
	v_mul_f32_e32 v217, 0x40400000, v117
	v_exp_f32_e32 v214, v214
	v_exp_f32_e32 v215, v215
	v_exp_f32_e32 v216, v216
	v_exp_f32_e32 v217, v217
	s_nop 0
	v_readfirstlane_b32 s90, v214
	v_readfirstlane_b32 s91, v215
	v_readfirstlane_b32 s92, v216
	v_readfirstlane_b32 s93, v217
	v_readfirstlane_b32 s94, v82
	v_add_u32_e32 v214, 0x4800, v79
	v_add_u32_e32 v215, 0x6800, v80
	s_waitcnt vmcnt(4)
	ds_write_b128 v214, v[224:227]
	ds_write2_b64 v215, v[228:229], v[230:231] offset0:128 offset1:130
	v_add_u32_e32 v214, 0x4800, v214
	v_add_u32_e32 v215, 0x4800, v215
	s_waitcnt vmcnt(2)
	ds_write_b128 v214, v[232:235]
	ds_write2_b64 v215, v[236:237], v[238:239] offset0:128 offset1:130
	v_add_u32_e32 v214, 0x4800, v214
	v_add_u32_e32 v215, 0x4800, v215
	s_waitcnt vmcnt(0)
	ds_write_b128 v214, v[240:243]
	ds_write2_b64 v215, v[244:245], v[246:247] offset0:128 offset1:130
	s_waitcnt lgkmcnt(0)
	s_barrier
	s_branch .LBB0_1184
.Lret_lean_f:
	s_and_b32 s0, s6, 1
	s_mul_i32 s1, s6, 0x4800
	v_add_u32_e32 v223, s1, v81
	s_nop 0
	s_nop 0
	ds_read_b128 v[182:185], v223
	ds_read_b128 v[186:189], v223 offset:32
	ds_read_b128 v[190:193], v223 offset:64
	ds_read_b128 v[194:197], v223 offset:96
	ds_read_b128 v[198:201], v223 offset:4608
	ds_read_b128 v[202:205], v223 offset:4640
	ds_read_b128 v[206:209], v223 offset:4672
	ds_read_b128 v[210:213], v223 offset:4704
	s_xor_b32 s0, s0, 1
	s_mulk_i32 s0, 0x4800
	s_add_i32 s6, s6, 1
	v_lshl_add_u64 v[74:75], v[74:75], 0, s[30:31]
	v_lshl_add_u64 v[76:77], v[76:77], 0, s[8:9]
	v_add_u32_e32 v214, s20, v82
	v_add_u32_e32 v214, 0xffffffc5, v214
	v_cvt_f32_i32_e32 v214, v214
	v_mul_f32_e32 v214, v115, v214
	v_exp_f32_e32 v214, v214
	s_waitcnt lgkmcnt(7)
	v_mfma_f32_32x32x16_bf16 v[48:63], v[182:185], v[108:111], 0
	s_waitcnt lgkmcnt(6)
	v_mfma_f32_32x32x16_bf16 v[48:63], v[186:189], v[104:107], v[48:63]
	s_waitcnt lgkmcnt(5)
	v_mfma_f32_32x32x16_bf16 v[48:63], v[190:193], v[100:103], v[48:63]
	s_waitcnt lgkmcnt(4)
	v_mfma_f32_32x32x16_bf16 v[48:63], v[194:197], v[96:99], v[48:63]
	s_waitcnt lgkmcnt(3)
	v_mfma_f32_32x32x16_bf16 v[32:47], v[198:201], v[108:111], 0
	s_waitcnt lgkmcnt(2)
	v_mfma_f32_32x32x16_bf16 v[32:47], v[202:205], v[104:107], v[32:47]
	s_waitcnt lgkmcnt(1)
	v_mfma_f32_32x32x16_bf16 v[32:47], v[206:209], v[100:103], v[32:47]
	s_waitcnt lgkmcnt(0)
	v_mfma_f32_32x32x16_bf16 v[32:47], v[210:213], v[96:99], v[32:47]
	v_mul_f32_e32 v214, 0x3e000000, v214
	v_add3_u32 v223, s1, v78, v130
	ds_read_b128 v[182:185], v223 offset:9216
	ds_read_b128 v[186:189], v223 offset:13824
	ds_read_b128 v[190:193], v223 offset:9248
	ds_read_b128 v[194:197], v223 offset:13856
	ds_read_b128 v[198:201], v223 offset:9280
	ds_read_b128 v[202:205], v223 offset:13888
	ds_read_b128 v[206:209], v223 offset:9312
	ds_read_b128 v[210:213], v223 offset:13920
	v_mul_f32_e32 v215, s70, v214
	v_mul_f32_e32 v216, s71, v214
	v_mul_f32_e32 v217, s72, v214
	v_mul_f32_e32 v218, s73, v214
	v_mul_f32_e32 v219, s74, v214
	v_mul_f32_e32 v220, s75, v214
	v_mul_f32_e32 v221, s76, v214
	v_mul_f32_e32 v222, s77, v214
	s_nop 3
	v_mul_f32_e32 v48, v215, v48
	v_mul_f32_e32 v49, v215, v49
	v_mul_f32_e32 v50, v215, v50
	v_mul_f32_e32 v51, v215, v51
	v_mul_f32_e32 v52, v216, v52
	v_mul_f32_e32 v53, v216, v53
	v_mul_f32_e32 v54, v216, v54
	v_mul_f32_e32 v55, v216, v55
	v_mul_f32_e32 v56, v217, v56
	v_mul_f32_e32 v57, v217, v57
	v_mul_f32_e32 v58, v217, v58
	v_mul_f32_e32 v59, v217, v59
	v_mul_f32_e32 v60, v218, v60
	v_mul_f32_e32 v61, v218, v61
	v_mul_f32_e32 v62, v218, v62
	v_mul_f32_e32 v63, v218, v63
	v_mul_f32_e32 v48, s78, v48
	v_mul_f32_e32 v49, s79, v49
	v_mul_f32_e32 v50, s80, v50
	v_mul_f32_e32 v51, s81, v51
	v_mul_f32_e32 v52, s78, v52
	v_mul_f32_e32 v53, s79, v53
	v_mul_f32_e32 v54, s80, v54
	v_mul_f32_e32 v55, s81, v55
	v_mul_f32_e32 v56, s78, v56
	v_mul_f32_e32 v57, s79, v57
	v_mul_f32_e32 v58, s80, v58
	v_mul_f32_e32 v59, s81, v59
	v_mul_f32_e32 v60, s78, v60
	v_mul_f32_e32 v61, s79, v61
	v_mul_f32_e32 v62, s80, v62
	v_mul_f32_e32 v63, s81, v63
	v_cvt_pk_bf16_f32 v48, v48, v49
	v_cvt_pk_bf16_f32 v49, v50, v51
	v_cvt_pk_bf16_f32 v50, v52, v53
	v_cvt_pk_bf16_f32 v51, v54, v55
	v_cvt_pk_bf16_f32 v56, v56, v57
	v_cvt_pk_bf16_f32 v57, v58, v59
	v_cvt_pk_bf16_f32 v58, v60, v61
	v_cvt_pk_bf16_f32 v59, v62, v63
	s_waitcnt lgkmcnt(6)
	v_mfma_f32_32x32x16_bf16 v[0:15], v[182:185], v[48:51], v[0:15]
	v_mfma_f32_32x32x16_bf16 v[16:31], v[186:189], v[48:51], v[16:31]
	v_mul_f32_e32 v32, v219, v32
	v_mul_f32_e32 v33, v219, v33
	v_mul_f32_e32 v34, v219, v34
	v_mul_f32_e32 v35, v219, v35
	v_mul_f32_e32 v36, v220, v36
	v_mul_f32_e32 v37, v220, v37
	v_mul_f32_e32 v38, v220, v38
	v_mul_f32_e32 v39, v220, v39
	v_mul_f32_e32 v40, v221, v40
	v_mul_f32_e32 v41, v221, v41
	v_mul_f32_e32 v42, v221, v42
	v_mul_f32_e32 v43, v221, v43
	v_mul_f32_e32 v44, v222, v44
	v_mul_f32_e32 v45, v222, v45
	v_mul_f32_e32 v46, v222, v46
	v_mul_f32_e32 v47, v222, v47
	v_mul_f32_e32 v32, s78, v32
	v_mul_f32_e32 v33, s79, v33
	v_mul_f32_e32 v34, s80, v34
	v_mul_f32_e32 v35, s81, v35
	v_mul_f32_e32 v36, s78, v36
	v_mul_f32_e32 v37, s79, v37
	v_mul_f32_e32 v38, s80, v38
	v_mul_f32_e32 v39, s81, v39
	v_mul_f32_e32 v40, s78, v40
	v_mul_f32_e32 v41, s79, v41
	v_mul_f32_e32 v42, s80, v42
	v_mul_f32_e32 v43, s81, v43
	v_mul_f32_e32 v44, s78, v44
	v_mul_f32_e32 v45, s79, v45
	v_mul_f32_e32 v46, s80, v46
	v_mul_f32_e32 v47, s81, v47
	s_waitcnt lgkmcnt(4)
	v_mfma_f32_32x32x16_bf16 v[0:15], v[190:193], v[56:59], v[0:15]
	v_mfma_f32_32x32x16_bf16 v[16:31], v[194:197], v[56:59], v[16:31]
	v_cvt_pk_bf16_f32 v32, v32, v33
	v_cvt_pk_bf16_f32 v33, v34, v35
	v_cvt_pk_bf16_f32 v34, v36, v37
	v_cvt_pk_bf16_f32 v35, v38, v39
	v_cvt_pk_bf16_f32 v40, v40, v41
	v_cvt_pk_bf16_f32 v41, v42, v43
	v_cvt_pk_bf16_f32 v42, v44, v45
	v_cvt_pk_bf16_f32 v43, v46, v47
	s_waitcnt lgkmcnt(2)
	v_mfma_f32_32x32x16_bf16 v[0:15], v[198:201], v[32:35], v[0:15]
	v_mfma_f32_32x32x16_bf16 v[16:31], v[202:205], v[32:35], v[16:31]
	s_waitcnt lgkmcnt(0)
	v_mfma_f32_32x32x16_bf16 v[0:15], v[206:209], v[40:43], v[0:15]
	v_mfma_f32_32x32x16_bf16 v[16:31], v[210:213], v[40:43], v[16:31]
	s_sub_i32 s20, s20, 64
	s_cmpk_eq_i32 s20, 0xff40
	s_branch .Lret_tail
.Lret_lean_b:
	s_and_b32 s0, s6, 1
	s_mul_i32 s1, s6, 0x4800
	v_add_u32_e32 v223, s1, v81
	s_nop 0
	s_nop 0
	ds_read_b128 v[182:185], v223
	ds_read_b128 v[186:189], v223 offset:32
	ds_read_b128 v[190:193], v223 offset:64
	ds_read_b128 v[194:197], v223 offset:96
	ds_read_b128 v[198:201], v223 offset:4608
	ds_read_b128 v[202:205], v223 offset:4640
	ds_read_b128 v[206:209], v223 offset:4672
	ds_read_b128 v[210:213], v223 offset:4704
	s_xor_b32 s0, s0, 1
	s_mulk_i32 s0, 0x4800
	s_add_i32 s6, s6, 1
	v_lshl_add_u64 v[74:75], v[74:75], 0, s[30:31]
	v_lshl_add_u64 v[76:77], v[76:77], 0, s[8:9]
	v_add_u32_e32 v214, s20, v82
	v_sub_u32_e32 v214, 0, v214
	v_cvt_f32_i32_e32 v214, v214
	v_mul_f32_e32 v214, v117, v214
	v_exp_f32_e32 v214, v214
	s_waitcnt lgkmcnt(7)
	v_mfma_f32_32x32x16_bf16 v[48:63], v[182:185], v[108:111], 0
	s_waitcnt lgkmcnt(6)
	v_mfma_f32_32x32x16_bf16 v[48:63], v[186:189], v[104:107], v[48:63]
	s_waitcnt lgkmcnt(5)
	v_mfma_f32_32x32x16_bf16 v[48:63], v[190:193], v[100:103], v[48:63]
	s_waitcnt lgkmcnt(4)
	v_mfma_f32_32x32x16_bf16 v[48:63], v[194:197], v[96:99], v[48:63]
	s_waitcnt lgkmcnt(3)
	v_mfma_f32_32x32x16_bf16 v[32:47], v[198:201], v[108:111], 0
	s_waitcnt lgkmcnt(2)
	v_mfma_f32_32x32x16_bf16 v[32:47], v[202:205], v[104:107], v[32:47]
	s_waitcnt lgkmcnt(1)
	v_mfma_f32_32x32x16_bf16 v[32:47], v[206:209], v[100:103], v[32:47]
	s_waitcnt lgkmcnt(0)
	v_mfma_f32_32x32x16_bf16 v[32:47], v[210:213], v[96:99], v[32:47]
	v_mul_f32_e32 v214, 0x3e000000, v214
	v_add3_u32 v223, s1, v78, v130
	ds_read_b128 v[182:185], v223 offset:9216
	ds_read_b128 v[186:189], v223 offset:13824
	ds_read_b128 v[190:193], v223 offset:9248
	ds_read_b128 v[194:197], v223 offset:13856
	ds_read_b128 v[198:201], v223 offset:9280
	ds_read_b128 v[202:205], v223 offset:13888
	ds_read_b128 v[206:209], v223 offset:9312
	ds_read_b128 v[210:213], v223 offset:13920
	v_mul_f32_e32 v215, s82, v214
	v_mul_f32_e32 v216, s83, v214
	v_mul_f32_e32 v217, s84, v214
	v_mul_f32_e32 v218, s85, v214
	v_mul_f32_e32 v219, s86, v214
	v_mul_f32_e32 v220, s87, v214
	v_mul_f32_e32 v221, s88, v214
	v_mul_f32_e32 v222, s89, v214
	s_nop 3
	v_mul_f32_e32 v48, v215, v48
	v_mul_f32_e32 v49, v215, v49
	v_mul_f32_e32 v50, v215, v50
	v_mul_f32_e32 v51, v215, v51
	v_mul_f32_e32 v52, v216, v52
	v_mul_f32_e32 v53, v216, v53
	v_mul_f32_e32 v54, v216, v54
	v_mul_f32_e32 v55, v216, v55
	v_mul_f32_e32 v56, v217, v56
	v_mul_f32_e32 v57, v217, v57
	v_mul_f32_e32 v58, v217, v58
	v_mul_f32_e32 v59, v217, v59
	v_mul_f32_e32 v60, v218, v60
	v_mul_f32_e32 v61, v218, v61
	v_mul_f32_e32 v62, v218, v62
	v_mul_f32_e32 v63, v218, v63
	v_mul_f32_e32 v48, s90, v48
	v_mul_f32_e32 v49, s91, v49
	v_mul_f32_e32 v50, s92, v50
	v_mul_f32_e32 v51, s93, v51
	v_mul_f32_e32 v52, s90, v52
	v_mul_f32_e32 v53, s91, v53
	v_mul_f32_e32 v54, s92, v54
	v_mul_f32_e32 v55, s93, v55
	v_mul_f32_e32 v56, s90, v56
	v_mul_f32_e32 v57, s91, v57
	v_mul_f32_e32 v58, s92, v58
	v_mul_f32_e32 v59, s93, v59
	v_mul_f32_e32 v60, s90, v60
	v_mul_f32_e32 v61, s91, v61
	v_mul_f32_e32 v62, s92, v62
	v_mul_f32_e32 v63, s93, v63
	v_cvt_pk_bf16_f32 v48, v48, v49
	v_cvt_pk_bf16_f32 v49, v50, v51
	v_cvt_pk_bf16_f32 v50, v52, v53
	v_cvt_pk_bf16_f32 v51, v54, v55
	v_cvt_pk_bf16_f32 v56, v56, v57
	v_cvt_pk_bf16_f32 v57, v58, v59
	v_cvt_pk_bf16_f32 v58, v60, v61
	v_cvt_pk_bf16_f32 v59, v62, v63
	s_waitcnt lgkmcnt(6)
	v_mfma_f32_32x32x16_bf16 v[0:15], v[182:185], v[48:51], v[0:15]
	v_mfma_f32_32x32x16_bf16 v[16:31], v[186:189], v[48:51], v[16:31]
	v_mul_f32_e32 v32, v219, v32
	v_mul_f32_e32 v33, v219, v33
	v_mul_f32_e32 v34, v219, v34
	v_mul_f32_e32 v35, v219, v35
	v_mul_f32_e32 v36, v220, v36
	v_mul_f32_e32 v37, v220, v37
	v_mul_f32_e32 v38, v220, v38
	v_mul_f32_e32 v39, v220, v39
	v_mul_f32_e32 v40, v221, v40
	v_mul_f32_e32 v41, v221, v41
	v_mul_f32_e32 v42, v221, v42
	v_mul_f32_e32 v43, v221, v43
	v_mul_f32_e32 v44, v222, v44
	v_mul_f32_e32 v45, v222, v45
	v_mul_f32_e32 v46, v222, v46
	v_mul_f32_e32 v47, v222, v47
	v_mul_f32_e32 v32, s90, v32
	v_mul_f32_e32 v33, s91, v33
	v_mul_f32_e32 v34, s92, v34
	v_mul_f32_e32 v35, s93, v35
	v_mul_f32_e32 v36, s90, v36
	v_mul_f32_e32 v37, s91, v37
	v_mul_f32_e32 v38, s92, v38
	v_mul_f32_e32 v39, s93, v39
	v_mul_f32_e32 v40, s90, v40
	v_mul_f32_e32 v41, s91, v41
	v_mul_f32_e32 v42, s92, v42
	v_mul_f32_e32 v43, s93, v43
	v_mul_f32_e32 v44, s90, v44
	v_mul_f32_e32 v45, s91, v45
	v_mul_f32_e32 v46, s92, v46
	v_mul_f32_e32 v47, s93, v47
	s_waitcnt lgkmcnt(4)
	v_mfma_f32_32x32x16_bf16 v[0:15], v[190:193], v[56:59], v[0:15]
	v_mfma_f32_32x32x16_bf16 v[16:31], v[194:197], v[56:59], v[16:31]
	v_cvt_pk_bf16_f32 v32, v32, v33
	v_cvt_pk_bf16_f32 v33, v34, v35
	v_cvt_pk_bf16_f32 v34, v36, v37
	v_cvt_pk_bf16_f32 v35, v38, v39
	v_cvt_pk_bf16_f32 v40, v40, v41
	v_cvt_pk_bf16_f32 v41, v42, v43
	v_cvt_pk_bf16_f32 v42, v44, v45
	v_cvt_pk_bf16_f32 v43, v46, v47
	s_waitcnt lgkmcnt(2)
	v_mfma_f32_32x32x16_bf16 v[0:15], v[198:201], v[32:35], v[0:15]
	v_mfma_f32_32x32x16_bf16 v[16:31], v[202:205], v[32:35], v[16:31]
	s_waitcnt lgkmcnt(0)
	v_mfma_f32_32x32x16_bf16 v[0:15], v[206:209], v[40:43], v[0:15]
	v_mfma_f32_32x32x16_bf16 v[16:31], v[210:213], v[40:43], v[16:31]
	s_sub_i32 s20, s20, 64
	s_cmpk_eq_i32 s20, 0xff40
	s_branch .Lret_tail
.LBB0_1184:
	s_add_i32 s95, s94, s20
	s_cmp_ge_i32 s95, 64
	s_cbranch_scc1 .Lret_lean_f
	s_cmp_le_i32 s95, -32
	s_cbranch_scc1 .Lret_lean_b
	s_and_b32 s0, s6, 1
	s_mul_i32 s1, s6, 0x4800
	s_add_i32 s1, s1, 0
	v_add_u32_e32 v83, s1, v81
	s_nop 0
	s_nop 0
	ds_read_b128 v[32:35], v83 offset:4608
	ds_read_b128 v[36:39], v83
	ds_read_b128 v[84:87], v83 offset:32
	ds_read_b128 v[88:91], v83 offset:4640
	s_xor_b32 s0, s0, 1
	s_waitcnt lgkmcnt(2)
	v_mfma_f32_32x32x16_bf16 v[48:63], v[36:39], v[108:111], 0
	s_mulk_i32 s0, 0x4800
	s_add_i32 s0, s0, 0
	s_add_i32 s6, s6, 1
	v_lshl_add_u64 v[74:75], v[74:75], 0, s[30:31]
	v_lshl_add_u64 v[76:77], v[76:77], 0, s[8:9]
	v_mfma_f32_32x32x16_bf16 v[32:47], v[32:35], v[108:111], 0
	s_waitcnt lgkmcnt(1)
	v_mfma_f32_32x32x16_bf16 v[48:63], v[84:87], v[104:107], v[48:63]
	s_waitcnt lgkmcnt(0)
	v_mfma_f32_32x32x16_bf16 v[32:47], v[88:91], v[104:107], v[32:47]
	ds_read_b128 v[84:87], v83 offset:64
	ds_read_b128 v[88:91], v83 offset:4672
	s_waitcnt lgkmcnt(1)
	v_mfma_f32_32x32x16_bf16 v[48:63], v[84:87], v[100:103], v[48:63]
	s_waitcnt lgkmcnt(0)
	v_mfma_f32_32x32x16_bf16 v[32:47], v[88:91], v[100:103], v[32:47]
	ds_read_b128 v[84:87], v83 offset:96
	ds_read_b128 v[88:91], v83 offset:4704
	v_add_u32_e32 v83, s20, v82
	v_cmp_gt_i32_e32 vcc, 0, v83
	s_sub_i32 s20, s20, 64
	s_cmpk_eq_i32 s20, 0xff40
	s_waitcnt lgkmcnt(1)
	v_mfma_f32_32x32x16_bf16 v[48:63], v[84:87], v[96:99], v[48:63]
	v_sub_u32_e32 v84, 0, v83
	v_max_i32_e32 v84, v83, v84
	v_cvt_f32_u32_e32 v84, v84
	v_cndmask_b32_e32 v86, v115, v117, vcc
	v_subrev_u32_e32 v85, 32, v83
	v_cmp_gt_i32_e32 vcc, 0, v85
	v_mul_f32_e32 v84, v86, v84
	v_sub_u32_e32 v86, 32, v83
	v_max_i32_e32 v86, v85, v86
	v_cvt_f32_u32_e32 v86, v86
	v_cndmask_b32_e32 v85, v115, v117, vcc
	s_waitcnt lgkmcnt(0)
	v_mfma_f32_32x32x16_bf16 v[32:47], v[88:91], v[96:99], v[32:47]
	v_sub_u32_e32 v88, 1, v83
	v_mul_f32_e32 v85, v85, v86
	v_exp_f32_e32 v86, v85
	v_add_u32_e32 v85, -1, v83
	v_max_i32_e32 v88, v85, v88
	v_cvt_f32_u32_e32 v88, v88
	v_cmp_gt_i32_e32 vcc, 0, v85
	v_subrev_u32_e32 v87, 33, v83
	v_exp_f32_e32 v84, v84
	v_cndmask_b32_e32 v85, v115, v117, vcc
	v_mul_f32_e32 v85, v85, v88
	v_sub_u32_e32 v88, 33, v83
	v_max_i32_e32 v88, v87, v88
	v_cvt_f32_u32_e32 v88, v88
	v_cmp_gt_i32_e32 vcc, 0, v87
	v_exp_f32_e32 v85, v85
	s_nop 0
	v_cndmask_b32_e32 v87, v115, v117, vcc
	v_mul_f32_e32 v87, v87, v88
	v_exp_f32_e32 v87, v87
	v_pk_mul_f32 v[84:85], v[84:85], s[2:3] op_sel_hi:[1,0]
	v_sub_u32_e32 v88, 3, v83
	v_pk_mul_f32 v[48:49], v[84:85], v[48:49]
	v_pk_mul_f32 v[84:85], v[86:87], s[2:3] op_sel_hi:[1,0]
	v_sub_u32_e32 v86, 2, v83
	v_pk_mul_f32 v[32:33], v[84:85], v[32:33]
	v_add_u32_e32 v84, -2, v83
	v_max_i32_e32 v86, v84, v86
	v_cvt_f32_u32_e32 v86, v86
	v_cmp_gt_i32_e32 vcc, 0, v84
	v_subrev_u32_e32 v85, 34, v83
	v_subrev_u32_e32 v87, 35, v83
	v_cndmask_b32_e32 v84, v115, v117, vcc
	v_mul_f32_e32 v84, v84, v86
	v_sub_u32_e32 v86, 34, v83
	v_max_i32_e32 v86, v85, v86
	v_cvt_f32_u32_e32 v86, v86
	v_cmp_gt_i32_e32 vcc, 0, v85
	v_exp_f32_e32 v84, v84
	v_cvt_pk_bf16_f32 v32, v32, v33
	v_cndmask_b32_e32 v85, v115, v117, vcc
	v_mul_f32_e32 v85, v85, v86
	v_exp_f32_e32 v86, v85
	v_add_u32_e32 v85, -3, v83
	v_max_i32_e32 v88, v85, v88
	v_cvt_f32_u32_e32 v88, v88
	v_cmp_gt_i32_e32 vcc, 0, v85
	s_nop 1
	v_cndmask_b32_e32 v85, v115, v117, vcc
	v_mul_f32_e32 v85, v85, v88
	v_sub_u32_e32 v88, 35, v83
	v_max_i32_e32 v88, v87, v88
	v_cvt_f32_u32_e32 v88, v88
	v_cmp_gt_i32_e32 vcc, 0, v87
	v_exp_f32_e32 v85, v85
	s_nop 0
	v_cndmask_b32_e32 v87, v115, v117, vcc
	v_mul_f32_e32 v87, v87, v88
	v_exp_f32_e32 v87, v87
	v_pk_mul_f32 v[84:85], v[84:85], s[2:3] op_sel_hi:[1,0]
	v_sub_u32_e32 v88, 9, v83
	v_pk_mul_f32 v[50:51], v[84:85], v[50:51]
	v_pk_mul_f32 v[84:85], v[86:87], s[2:3] op_sel_hi:[1,0]
	v_sub_u32_e32 v86, 8, v83
	v_pk_mul_f32 v[84:85], v[84:85], v[34:35]
	v_add_u32_e32 v34, -8, v83
	v_max_i32_e32 v86, v34, v86
	v_cvt_f32_u32_e32 v86, v86
	v_cmp_gt_i32_e32 vcc, 0, v34
	v_subrev_u32_e32 v35, 40, v83
	v_subrev_u32_e32 v87, 41, v83
	v_cndmask_b32_e32 v34, v115, v117, vcc
	v_mul_f32_e32 v34, v34, v86
	v_sub_u32_e32 v86, 40, v83
	v_max_i32_e32 v86, v35, v86
	v_cvt_f32_u32_e32 v86, v86
	v_cmp_gt_i32_e32 vcc, 0, v35
	v_exp_f32_e32 v34, v34
	v_cvt_pk_bf16_f32 v33, v84, v85
	v_cndmask_b32_e32 v35, v115, v117, vcc
	v_mul_f32_e32 v35, v35, v86
	v_exp_f32_e32 v86, v35
	v_add_u32_e32 v35, -9, v83
	v_max_i32_e32 v88, v35, v88
	v_cvt_f32_u32_e32 v88, v88
	v_cmp_gt_i32_e32 vcc, 0, v35
	s_nop 1
	v_cndmask_b32_e32 v35, v115, v117, vcc
	v_mul_f32_e32 v35, v35, v88
	v_sub_u32_e32 v88, 41, v83
	v_max_i32_e32 v88, v87, v88
	v_cvt_f32_u32_e32 v88, v88
	v_cmp_gt_i32_e32 vcc, 0, v87
	v_exp_f32_e32 v35, v35
	s_nop 0
	v_cndmask_b32_e32 v87, v115, v117, vcc
	v_mul_f32_e32 v87, v87, v88
	v_exp_f32_e32 v87, v87
	v_pk_mul_f32 v[34:35], v[34:35], s[2:3] op_sel_hi:[1,0]
	v_sub_u32_e32 v88, 11, v83
	v_pk_mul_f32 v[52:53], v[34:35], v[52:53]
	v_pk_mul_f32 v[34:35], v[86:87], s[2:3] op_sel_hi:[1,0]
	s_nop 0
	v_pk_mul_f32 v[86:87], v[34:35], v[36:37]
	v_add_u32_e32 v34, -10, v83
	v_sub_u32_e32 v36, 10, v83
	v_max_i32_e32 v36, v34, v36
	v_cvt_f32_u32_e32 v36, v36
	v_cmp_gt_i32_e32 vcc, 0, v34
	v_subrev_u32_e32 v35, 42, v83
	v_subrev_u32_e32 v37, 43, v83
	v_cndmask_b32_e32 v34, v115, v117, vcc
	v_mul_f32_e32 v34, v34, v36
	v_sub_u32_e32 v36, 42, v83
	v_max_i32_e32 v36, v35, v36
	v_cvt_f32_u32_e32 v36, v36
	v_cmp_gt_i32_e32 vcc, 0, v35
	v_exp_f32_e32 v34, v34
	s_nop 0
	v_cndmask_b32_e32 v35, v115, v117, vcc
	v_mul_f32_e32 v35, v35, v36
	v_exp_f32_e32 v36, v35
	v_add_u32_e32 v35, -11, v83
	v_max_i32_e32 v88, v35, v88
	v_cvt_f32_u32_e32 v88, v88
	v_cmp_gt_i32_e32 vcc, 0, v35
	s_nop 1
	v_cndmask_b32_e32 v35, v115, v117, vcc
	v_mul_f32_e32 v35, v35, v88
	v_sub_u32_e32 v88, 43, v83
	v_max_i32_e32 v88, v37, v88
	v_cvt_f32_u32_e32 v88, v88
	v_cmp_gt_i32_e32 vcc, 0, v37
	v_exp_f32_e32 v35, v35
	s_nop 0
	v_cndmask_b32_e32 v37, v115, v117, vcc
	v_mul_f32_e32 v37, v37, v88
	v_exp_f32_e32 v37, v37
	v_pk_mul_f32 v[34:35], v[34:35], s[2:3] op_sel_hi:[1,0]
	s_nop 0
	v_pk_mul_f32 v[54:55], v[34:35], v[54:55]
	v_pk_mul_f32 v[34:35], v[36:37], s[2:3] op_sel_hi:[1,0]
	v_sub_u32_e32 v36, 16, v83
	v_pk_mul_f32 v[88:89], v[34:35], v[38:39]
	v_add_u32_e32 v34, -16, v83
	v_max_i32_e32 v36, v34, v36
	v_cvt_f32_u32_e32 v36, v36
	v_cmp_gt_i32_e32 vcc, 0, v34
	v_subrev_u32_e32 v35, 48, v83
	v_sub_u32_e32 v38, 17, v83
	v_cndmask_b32_e32 v34, v115, v117, vcc
	v_mul_f32_e32 v34, v34, v36
	v_sub_u32_e32 v36, 48, v83
	v_max_i32_e32 v36, v35, v36
	v_cvt_f32_u32_e32 v36, v36
	v_cmp_gt_i32_e32 vcc, 0, v35
	v_subrev_u32_e32 v37, 49, v83
	v_exp_f32_e32 v34, v34
	v_cndmask_b32_e32 v35, v115, v117, vcc
	v_mul_f32_e32 v35, v35, v36
	v_exp_f32_e32 v36, v35
	v_subrev_u32_e32 v35, 17, v83
	v_max_i32_e32 v38, v35, v38
	v_cvt_f32_u32_e32 v38, v38
	v_cmp_gt_i32_e32 vcc, 0, v35
	s_nop 1
	v_cndmask_b32_e32 v35, v115, v117, vcc
	v_mul_f32_e32 v35, v35, v38
	v_sub_u32_e32 v38, 49, v83
	v_max_i32_e32 v38, v37, v38
	v_cvt_f32_u32_e32 v38, v38
	v_cmp_gt_i32_e32 vcc, 0, v37
	v_exp_f32_e32 v35, v35
	s_nop 0
	v_cndmask_b32_e32 v37, v115, v117, vcc
	v_mul_f32_e32 v37, v37, v38
	v_exp_f32_e32 v37, v37
	v_pk_mul_f32 v[34:35], v[34:35], s[2:3] op_sel_hi:[1,0]
	v_sub_u32_e32 v38, 19, v83
	v_pk_mul_f32 v[56:57], v[34:35], v[56:57]
	v_pk_mul_f32 v[34:35], v[36:37], s[2:3] op_sel_hi:[1,0]
	v_sub_u32_e32 v36, 18, v83
	v_pk_mul_f32 v[90:91], v[34:35], v[40:41]
	v_subrev_u32_e32 v34, 18, v83
	v_max_i32_e32 v36, v34, v36
	v_cvt_f32_u32_e32 v36, v36
	v_cmp_gt_i32_e32 vcc, 0, v34
	v_subrev_u32_e32 v35, 50, v83
	v_subrev_u32_e32 v37, 51, v83
	v_cndmask_b32_e32 v34, v115, v117, vcc
	v_mul_f32_e32 v34, v34, v36
	v_sub_u32_e32 v36, 50, v83
	v_max_i32_e32 v36, v35, v36
	v_cvt_f32_u32_e32 v36, v36
	v_cmp_gt_i32_e32 vcc, 0, v35
	v_exp_f32_e32 v34, v34
	s_nop 0
	v_cndmask_b32_e32 v35, v115, v117, vcc
	v_mul_f32_e32 v35, v35, v36
	v_exp_f32_e32 v36, v35
	v_subrev_u32_e32 v35, 19, v83
	v_max_i32_e32 v38, v35, v38
	v_cvt_f32_u32_e32 v38, v38
	v_cmp_gt_i32_e32 vcc, 0, v35
	s_nop 1
	v_cndmask_b32_e32 v35, v115, v117, vcc
	v_mul_f32_e32 v35, v35, v38
	v_sub_u32_e32 v38, 51, v83
	v_max_i32_e32 v38, v37, v38
	v_cvt_f32_u32_e32 v38, v38
	v_cmp_gt_i32_e32 vcc, 0, v37
	v_exp_f32_e32 v35, v35
	s_nop 0
	v_cndmask_b32_e32 v37, v115, v117, vcc
	v_mul_f32_e32 v37, v37, v38
	v_exp_f32_e32 v37, v37
	v_pk_mul_f32 v[34:35], v[34:35], s[2:3] op_sel_hi:[1,0]
	v_sub_u32_e32 v38, 25, v83
	v_pk_mul_f32 v[58:59], v[34:35], v[58:59]
	v_pk_mul_f32 v[34:35], v[36:37], s[2:3] op_sel_hi:[1,0]
	v_sub_u32_e32 v36, 24, v83
	v_pk_mul_f32 v[92:93], v[34:35], v[42:43]
	v_subrev_u32_e32 v34, 24, v83
	v_max_i32_e32 v36, v34, v36
	v_cvt_f32_u32_e32 v36, v36
	v_cmp_gt_i32_e32 vcc, 0, v34
	v_subrev_u32_e32 v35, 56, v83
	v_subrev_u32_e32 v37, 57, v83
	v_cndmask_b32_e32 v34, v115, v117, vcc
	v_mul_f32_e32 v34, v34, v36
	v_sub_u32_e32 v36, 56, v83
	v_max_i32_e32 v36, v35, v36
	v_cvt_f32_u32_e32 v36, v36
	v_cmp_gt_i32_e32 vcc, 0, v35
	v_exp_f32_e32 v34, v34
	s_nop 0
	v_cndmask_b32_e32 v35, v115, v117, vcc
	v_mul_f32_e32 v35, v35, v36
	v_exp_f32_e32 v36, v35
	v_subrev_u32_e32 v35, 25, v83
	v_max_i32_e32 v38, v35, v38
	v_cvt_f32_u32_e32 v38, v38
	v_cmp_gt_i32_e32 vcc, 0, v35
	s_nop 1
	v_cndmask_b32_e32 v35, v115, v117, vcc
	v_mul_f32_e32 v35, v35, v38
	v_sub_u32_e32 v38, 57, v83
	v_max_i32_e32 v38, v37, v38
	v_cvt_f32_u32_e32 v38, v38
	v_cmp_gt_i32_e32 vcc, 0, v37
	v_exp_f32_e32 v35, v35
	s_nop 0
	v_cndmask_b32_e32 v37, v115, v117, vcc
	v_mul_f32_e32 v37, v37, v38
	v_exp_f32_e32 v37, v37
	v_pk_mul_f32 v[34:35], v[34:35], s[2:3] op_sel_hi:[1,0]
	v_sub_u32_e32 v38, 27, v83
	v_pk_mul_f32 v[60:61], v[34:35], v[60:61]
	v_pk_mul_f32 v[34:35], v[36:37], s[2:3] op_sel_hi:[1,0]
	v_sub_u32_e32 v36, 26, v83
	v_pk_mul_f32 v[94:95], v[34:35], v[44:45]
	v_subrev_u32_e32 v34, 26, v83
	v_max_i32_e32 v36, v34, v36
	v_cvt_f32_u32_e32 v36, v36
	v_cmp_gt_i32_e32 vcc, 0, v34
	v_subrev_u32_e32 v35, 58, v83
	v_subrev_u32_e32 v37, 59, v83
	v_cndmask_b32_e32 v34, v115, v117, vcc
	v_mul_f32_e32 v34, v34, v36
	v_sub_u32_e32 v36, 58, v83
	v_max_i32_e32 v36, v35, v36
	v_cvt_f32_u32_e32 v36, v36
	v_cmp_gt_i32_e32 vcc, 0, v35
	v_exp_f32_e32 v34, v34
	s_nop 0
	v_cndmask_b32_e32 v35, v115, v117, vcc
	v_mul_f32_e32 v35, v35, v36
	v_exp_f32_e32 v36, v35
	v_subrev_u32_e32 v35, 27, v83
	v_max_i32_e32 v38, v35, v38
	v_cvt_f32_u32_e32 v38, v38
	v_cmp_gt_i32_e32 vcc, 0, v35
	s_nop 1
	v_cndmask_b32_e32 v35, v115, v117, vcc
	v_mul_f32_e32 v35, v35, v38
	v_sub_u32_e32 v38, 59, v83
	v_max_i32_e32 v38, v37, v38
	v_cvt_f32_u32_e32 v38, v38
	v_cmp_gt_i32_e32 vcc, 0, v37
	v_exp_f32_e32 v35, v35
	s_nop 0
	v_cndmask_b32_e32 v37, v115, v117, vcc
	v_mul_f32_e32 v37, v37, v38
	v_exp_f32_e32 v37, v37
	v_pk_mul_f32 v[34:35], v[34:35], s[2:3] op_sel_hi:[1,0]
	s_nop 0
	v_pk_mul_f32 v[62:63], v[34:35], v[62:63]
	v_pk_mul_f32 v[34:35], v[36:37], s[2:3] op_sel_hi:[1,0]
	v_cvt_pk_bf16_f32 v36, v52, v53
	v_pk_mul_f32 v[118:119], v[34:35], v[46:47]
	v_cvt_pk_bf16_f32 v35, v50, v51
	v_add3_u32 v50, s1, v78, v130
	v_cvt_pk_bf16_f32 v34, v48, v49
	ds_read_b128 v[38:41], v50 offset:13824
	ds_read_b128 v[42:45], v50 offset:9216
	ds_read_b128 v[46:49], v50 offset:9248
	v_cvt_pk_bf16_f32 v37, v54, v55
	s_waitcnt lgkmcnt(2)
	s_nop 0
	v_mfma_f32_32x32x16_bf16 v[16:31], v[38:41], v[34:37], v[16:31]
	ds_read_b128 v[38:41], v50 offset:13856
	s_waitcnt lgkmcnt(2)
	v_mfma_f32_32x32x16_bf16 v[0:15], v[42:45], v[34:37], v[0:15]
	v_cvt_pk_bf16_f32 v34, v56, v57
	v_cvt_pk_bf16_f32 v35, v58, v59
	v_cvt_pk_bf16_f32 v36, v60, v61
	v_cvt_pk_bf16_f32 v37, v62, v63
	s_waitcnt lgkmcnt(1)
	s_nop 0
	v_mfma_f32_32x32x16_bf16 v[0:15], v[46:49], v[34:37], v[0:15]
	s_waitcnt lgkmcnt(0)
	v_mfma_f32_32x32x16_bf16 v[16:31], v[38:41], v[34:37], v[16:31]
	ds_read_b128 v[36:39], v50 offset:9280
	ds_read_b128 v[40:43], v50 offset:13888
	v_cvt_pk_bf16_f32 v34, v86, v87
	v_cvt_pk_bf16_f32 v35, v88, v89
	s_waitcnt lgkmcnt(1)
	s_nop 0
	v_mfma_f32_32x32x16_bf16 v[0:15], v[36:39], v[32:35], v[0:15]
	s_waitcnt lgkmcnt(0)
	v_mfma_f32_32x32x16_bf16 v[16:31], v[40:43], v[32:35], v[16:31]
	ds_read_b128 v[36:39], v50 offset:9312
	ds_read_b128 v[40:43], v50 offset:13920
	v_cvt_pk_bf16_f32 v32, v90, v91
	v_cvt_pk_bf16_f32 v33, v92, v93
	v_cvt_pk_bf16_f32 v34, v94, v95
	v_cvt_pk_bf16_f32 v35, v118, v119
	s_waitcnt lgkmcnt(1)
	s_nop 0
	v_mfma_f32_32x32x16_bf16 v[0:15], v[36:39], v[32:35], v[0:15]
	s_waitcnt lgkmcnt(0)
	v_mfma_f32_32x32x16_bf16 v[16:31], v[40:43], v[32:35], v[16:31]
.Lret_tail:
	s_cbranch_scc0 .LBB0_1184
	v_add_u32_e32 v74, 0x9000, v81
	ds_read_b128 v[32:35], v74 offset:23040
	ds_read_b128 v[36:39], v74 offset:18432
	ds_read_b128 v[64:67], v74 offset:18464
	ds_read_b128 v[68:71], v74 offset:23072
	s_movk_i32 s0, 0xff3f
	s_cmp_eq_u64 s[4:5], 0
	s_waitcnt lgkmcnt(2)
	v_mfma_f32_32x32x16_bf16 v[48:63], v[36:39], v[108:111], 0
	v_mfma_f32_32x32x16_bf16 v[32:47], v[32:35], v[108:111], 0
	s_waitcnt lgkmcnt(1)
	v_mfma_f32_32x32x16_bf16 v[48:63], v[64:67], v[104:107], v[48:63]
	s_waitcnt lgkmcnt(0)
	v_mfma_f32_32x32x16_bf16 v[32:47], v[68:71], v[104:107], v[32:47]
	ds_read_b128 v[64:67], v74 offset:18496
	ds_read_b128 v[68:71], v74 offset:23104
	s_waitcnt lgkmcnt(1)
	v_mfma_f32_32x32x16_bf16 v[48:63], v[64:67], v[100:103], v[48:63]
	s_waitcnt lgkmcnt(0)
	v_mfma_f32_32x32x16_bf16 v[32:47], v[68:71], v[100:103], v[32:47]
	ds_read_b128 v[64:67], v74 offset:18528
	ds_read_b128 v[68:71], v74 offset:23136
	s_mov_b32 s95, 0x9000
	v_add3_u32 v74, s95, v78, v130
	s_waitcnt lgkmcnt(1)
	v_mfma_f32_32x32x16_bf16 v[48:63], v[64:67], v[96:99], v[48:63]
	v_or_b32_e32 v64, 0xc0, v114
	v_sub_u32_e32 v64, v116, v64
	v_sub_u32_e32 v66, 0, v64
	v_max_i32_e32 v66, v64, v66
	v_cvt_f32_u32_e32 v66, v66
	v_or_b32_e32 v65, 0xe0, v114
	v_cmp_gt_i32_e32 vcc, 0, v64
	v_sub_u32_e32 v65, v116, v65
	v_xad_u32 v67, v114, s0, v116
	v_cndmask_b32_e32 v64, v115, v117, vcc
	v_mul_f32_e32 v64, v64, v66
	v_sub_u32_e32 v66, 0, v65
	v_max_i32_e32 v66, v65, v66
	v_cvt_f32_u32_e32 v66, v66
	v_cmp_gt_i32_e32 vcc, 0, v65
	s_waitcnt lgkmcnt(0)
	v_mfma_f32_32x32x16_bf16 v[32:47], v[68:71], v[96:99], v[32:47]
	v_exp_f32_e32 v64, v64
	v_cndmask_b32_e32 v65, v115, v117, vcc
	v_mul_f32_e32 v65, v65, v66
	v_exp_f32_e32 v66, v65
	v_or_b32_e32 v65, 0xe1, v114
	v_sub_u32_e32 v68, v116, v65
	v_sub_u32_e32 v65, 0, v67
	v_max_i32_e32 v65, v67, v65
	v_cvt_f32_u32_e32 v65, v65
	v_cmp_gt_i32_e32 vcc, 0, v67
	s_nop 1
	v_cndmask_b32_e32 v67, v115, v117, vcc
	v_mul_f32_e32 v65, v67, v65
	v_sub_u32_e32 v67, 0, v68
	v_max_i32_e32 v67, v68, v67
	v_cvt_f32_u32_e32 v67, v67
	v_cmp_gt_i32_e32 vcc, 0, v68
	v_exp_f32_e32 v65, v65
	s_nop 0
	v_cndmask_b32_e32 v68, v115, v117, vcc
	v_mul_f32_e32 v67, v68, v67
	v_exp_f32_e32 v67, v67
	v_pk_mul_f32 v[64:65], v[64:65], s[2:3] op_sel_hi:[1,0]
	s_nop 0
	v_pk_mul_f32 v[48:49], v[64:65], v[48:49]
	v_pk_mul_f32 v[64:65], v[66:67], s[2:3] op_sel_hi:[1,0]
	v_or_b32_e32 v67, 0xe3, v114
	v_pk_mul_f32 v[32:33], v[64:65], v[32:33]
	v_or_b32_e32 v64, 0xc2, v114
	v_sub_u32_e32 v64, v116, v64
	v_sub_u32_e32 v66, 0, v64
	v_max_i32_e32 v66, v64, v66
	v_cvt_f32_u32_e32 v66, v66
	v_or_b32_e32 v65, 0xe2, v114
	v_cmp_gt_i32_e32 vcc, 0, v64
	v_sub_u32_e32 v65, v116, v65
	v_sub_u32_e32 v67, v116, v67
	v_cndmask_b32_e32 v64, v115, v117, vcc
	v_mul_f32_e32 v64, v64, v66
	v_sub_u32_e32 v66, 0, v65
	v_max_i32_e32 v66, v65, v66
	v_cvt_f32_u32_e32 v66, v66
	v_cmp_gt_i32_e32 vcc, 0, v65
	v_exp_f32_e32 v64, v64
	v_cvt_pk_bf16_f32 v48, v48, v49
	v_cndmask_b32_e32 v65, v115, v117, vcc
	v_mul_f32_e32 v65, v65, v66
	v_exp_f32_e32 v66, v65
	v_or_b32_e32 v65, 0xc3, v114
	v_sub_u32_e32 v65, v116, v65
	v_sub_u32_e32 v68, 0, v65
	v_max_i32_e32 v68, v65, v68
	v_cvt_f32_u32_e32 v68, v68
	v_cmp_gt_i32_e32 vcc, 0, v65
	v_cvt_pk_bf16_f32 v32, v32, v33
	s_nop 0
	v_cndmask_b32_e32 v65, v115, v117, vcc
	v_mul_f32_e32 v65, v65, v68
	v_sub_u32_e32 v68, 0, v67
	v_max_i32_e32 v68, v67, v68
	v_cvt_f32_u32_e32 v68, v68
	v_cmp_gt_i32_e32 vcc, 0, v67
	v_exp_f32_e32 v65, v65
	s_nop 0
	v_cndmask_b32_e32 v67, v115, v117, vcc
	v_mul_f32_e32 v67, v67, v68
	v_exp_f32_e32 v67, v67
	v_pk_mul_f32 v[64:65], v[64:65], s[2:3] op_sel_hi:[1,0]
	s_nop 0
	v_pk_mul_f32 v[50:51], v[64:65], v[50:51]
	v_pk_mul_f32 v[64:65], v[66:67], s[2:3] op_sel_hi:[1,0]
	v_or_b32_e32 v67, 0xe9, v114
	v_pk_mul_f32 v[34:35], v[64:65], v[34:35]
	v_or_b32_e32 v64, 0xc8, v114
	v_sub_u32_e32 v64, v116, v64
	v_sub_u32_e32 v66, 0, v64
	v_max_i32_e32 v66, v64, v66
	v_cvt_f32_u32_e32 v66, v66
	v_or_b32_e32 v65, 0xe8, v114
	v_cmp_gt_i32_e32 vcc, 0, v64
	v_sub_u32_e32 v65, v116, v65
	v_sub_u32_e32 v67, v116, v67
	v_cndmask_b32_e32 v64, v115, v117, vcc
	v_mul_f32_e32 v64, v64, v66
	v_sub_u32_e32 v66, 0, v65
	v_max_i32_e32 v66, v65, v66
	v_cvt_f32_u32_e32 v66, v66
	v_cmp_gt_i32_e32 vcc, 0, v65
	v_exp_f32_e32 v64, v64
	v_cvt_pk_bf16_f32 v49, v50, v51
	v_cndmask_b32_e32 v65, v115, v117, vcc
	v_mul_f32_e32 v65, v65, v66
	v_exp_f32_e32 v66, v65
	v_or_b32_e32 v65, 0xc9, v114
	v_sub_u32_e32 v65, v116, v65
	v_sub_u32_e32 v68, 0, v65
	v_max_i32_e32 v68, v65, v68
	v_cvt_f32_u32_e32 v68, v68
	v_cmp_gt_i32_e32 vcc, 0, v65
	v_cvt_pk_bf16_f32 v33, v34, v35
	s_nop 0
	v_cndmask_b32_e32 v65, v115, v117, vcc
	v_mul_f32_e32 v65, v65, v68
	v_sub_u32_e32 v68, 0, v67
	v_max_i32_e32 v68, v67, v68
	v_cvt_f32_u32_e32 v68, v68
	v_cmp_gt_i32_e32 vcc, 0, v67
	v_exp_f32_e32 v65, v65
	s_nop 0
	v_cndmask_b32_e32 v67, v115, v117, vcc
	v_mul_f32_e32 v67, v67, v68
	v_exp_f32_e32 v67, v67
	v_pk_mul_f32 v[64:65], v[64:65], s[2:3] op_sel_hi:[1,0]
	s_nop 0
	v_pk_mul_f32 v[52:53], v[64:65], v[52:53]
	v_pk_mul_f32 v[64:65], v[66:67], s[2:3] op_sel_hi:[1,0]
	v_or_b32_e32 v67, 0xeb, v114
	v_pk_mul_f32 v[36:37], v[64:65], v[36:37]
	v_or_b32_e32 v64, 0xca, v114
	v_sub_u32_e32 v64, v116, v64
	v_sub_u32_e32 v66, 0, v64
	v_max_i32_e32 v66, v64, v66
	v_cvt_f32_u32_e32 v66, v66
	v_or_b32_e32 v65, 0xea, v114
	v_cmp_gt_i32_e32 vcc, 0, v64
	v_sub_u32_e32 v65, v116, v65
	v_sub_u32_e32 v67, v116, v67
	v_cndmask_b32_e32 v64, v115, v117, vcc
	v_mul_f32_e32 v64, v64, v66
	v_sub_u32_e32 v66, 0, v65
	v_max_i32_e32 v66, v65, v66
	v_cvt_f32_u32_e32 v66, v66
	v_cmp_gt_i32_e32 vcc, 0, v65
	v_exp_f32_e32 v64, v64
	v_cvt_pk_bf16_f32 v50, v52, v53
	v_cndmask_b32_e32 v65, v115, v117, vcc
	v_mul_f32_e32 v65, v65, v66
	v_exp_f32_e32 v66, v65
	v_or_b32_e32 v65, 0xcb, v114
	v_sub_u32_e32 v65, v116, v65
	v_sub_u32_e32 v68, 0, v65
	v_max_i32_e32 v68, v65, v68
	v_cvt_f32_u32_e32 v68, v68
	v_cmp_gt_i32_e32 vcc, 0, v65
	v_cvt_pk_bf16_f32 v34, v36, v37
	s_nop 0
	v_cndmask_b32_e32 v65, v115, v117, vcc
	v_mul_f32_e32 v65, v65, v68
	v_sub_u32_e32 v68, 0, v67
	v_max_i32_e32 v68, v67, v68
	v_cvt_f32_u32_e32 v68, v68
	v_cmp_gt_i32_e32 vcc, 0, v67
	v_exp_f32_e32 v65, v65
	s_nop 0
	v_cndmask_b32_e32 v67, v115, v117, vcc
	v_mul_f32_e32 v67, v67, v68
	v_exp_f32_e32 v67, v67
	v_pk_mul_f32 v[64:65], v[64:65], s[2:3] op_sel_hi:[1,0]
	s_nop 0
	v_pk_mul_f32 v[54:55], v[64:65], v[54:55]
	v_pk_mul_f32 v[64:65], v[66:67], s[2:3] op_sel_hi:[1,0]
	v_or_b32_e32 v67, 0xf1, v114
	v_pk_mul_f32 v[38:39], v[64:65], v[38:39]
	v_or_b32_e32 v64, 0xd0, v114
	v_sub_u32_e32 v64, v116, v64
	v_sub_u32_e32 v66, 0, v64
	v_max_i32_e32 v66, v64, v66
	v_cvt_f32_u32_e32 v66, v66
	v_or_b32_e32 v65, 0xf0, v114
	v_cmp_gt_i32_e32 vcc, 0, v64
	v_sub_u32_e32 v65, v116, v65
	v_sub_u32_e32 v67, v116, v67
	v_cndmask_b32_e32 v64, v115, v117, vcc
	v_mul_f32_e32 v64, v64, v66
	v_sub_u32_e32 v66, 0, v65
	v_max_i32_e32 v66, v65, v66
	v_cvt_f32_u32_e32 v66, v66
	v_cmp_gt_i32_e32 vcc, 0, v65
	v_exp_f32_e32 v64, v64
	v_cvt_pk_bf16_f32 v51, v54, v55
	v_cndmask_b32_e32 v65, v115, v117, vcc
	v_mul_f32_e32 v65, v65, v66
	v_exp_f32_e32 v66, v65
	v_or_b32_e32 v65, 0xd1, v114
	v_sub_u32_e32 v65, v116, v65
	v_sub_u32_e32 v68, 0, v65
	v_max_i32_e32 v68, v65, v68
	v_cvt_f32_u32_e32 v68, v68
	v_cmp_gt_i32_e32 vcc, 0, v65
	v_cvt_pk_bf16_f32 v35, v38, v39
	s_nop 0
	v_cndmask_b32_e32 v65, v115, v117, vcc
	v_mul_f32_e32 v65, v65, v68
	v_sub_u32_e32 v68, 0, v67
	v_max_i32_e32 v68, v67, v68
	v_cvt_f32_u32_e32 v68, v68
	v_cmp_gt_i32_e32 vcc, 0, v67
	v_exp_f32_e32 v65, v65
	s_nop 0
	v_cndmask_b32_e32 v67, v115, v117, vcc
	v_mul_f32_e32 v67, v67, v68
	v_exp_f32_e32 v67, v67
	v_pk_mul_f32 v[64:65], v[64:65], s[2:3] op_sel_hi:[1,0]
	s_nop 0
	v_pk_mul_f32 v[56:57], v[64:65], v[56:57]
	v_pk_mul_f32 v[64:65], v[66:67], s[2:3] op_sel_hi:[1,0]
	v_or_b32_e32 v67, 0xf3, v114
	v_pk_mul_f32 v[40:41], v[64:65], v[40:41]
	v_or_b32_e32 v64, 0xd2, v114
	v_sub_u32_e32 v64, v116, v64
	v_sub_u32_e32 v66, 0, v64
	v_max_i32_e32 v66, v64, v66
	v_cvt_f32_u32_e32 v66, v66
	v_or_b32_e32 v65, 0xf2, v114
	v_cmp_gt_i32_e32 vcc, 0, v64
	v_sub_u32_e32 v65, v116, v65
	v_sub_u32_e32 v67, v116, v67
	v_cndmask_b32_e32 v64, v115, v117, vcc
	v_mul_f32_e32 v64, v64, v66
	v_sub_u32_e32 v66, 0, v65
	v_max_i32_e32 v66, v65, v66
	v_cvt_f32_u32_e32 v66, v66
	v_cmp_gt_i32_e32 vcc, 0, v65
	v_exp_f32_e32 v64, v64
	s_nop 0
	v_cndmask_b32_e32 v65, v115, v117, vcc
	v_mul_f32_e32 v65, v65, v66
	v_exp_f32_e32 v66, v65
	v_or_b32_e32 v65, 0xd3, v114
	v_sub_u32_e32 v65, v116, v65
	v_sub_u32_e32 v68, 0, v65
	v_max_i32_e32 v68, v65, v68
	v_cvt_f32_u32_e32 v68, v68
	v_cmp_gt_i32_e32 vcc, 0, v65
	s_nop 1
	v_cndmask_b32_e32 v65, v115, v117, vcc
	v_mul_f32_e32 v65, v65, v68
	v_sub_u32_e32 v68, 0, v67
	v_max_i32_e32 v68, v67, v68
	v_cvt_f32_u32_e32 v68, v68
	v_cmp_gt_i32_e32 vcc, 0, v67
	v_exp_f32_e32 v65, v65
	s_nop 0
	v_cndmask_b32_e32 v67, v115, v117, vcc
	v_mul_f32_e32 v67, v67, v68
	v_exp_f32_e32 v67, v67
	v_pk_mul_f32 v[64:65], v[64:65], s[2:3] op_sel_hi:[1,0]
	s_nop 0
	v_pk_mul_f32 v[58:59], v[64:65], v[58:59]
	v_pk_mul_f32 v[64:65], v[66:67], s[2:3] op_sel_hi:[1,0]
	v_or_b32_e32 v67, 0xf9, v114
	v_pk_mul_f32 v[42:43], v[64:65], v[42:43]
	v_or_b32_e32 v64, 0xd8, v114
	v_sub_u32_e32 v64, v116, v64
	v_sub_u32_e32 v66, 0, v64
	v_max_i32_e32 v66, v64, v66
	v_cvt_f32_u32_e32 v66, v66
	v_or_b32_e32 v65, 0xf8, v114
	v_cmp_gt_i32_e32 vcc, 0, v64
	v_sub_u32_e32 v65, v116, v65
	v_sub_u32_e32 v67, v116, v67
	v_cndmask_b32_e32 v64, v115, v117, vcc
	v_mul_f32_e32 v64, v64, v66
	v_sub_u32_e32 v66, 0, v65
	v_max_i32_e32 v66, v65, v66
	v_cvt_f32_u32_e32 v66, v66
	v_cmp_gt_i32_e32 vcc, 0, v65
	v_exp_f32_e32 v64, v64
	s_nop 0
	v_cndmask_b32_e32 v65, v115, v117, vcc
	v_mul_f32_e32 v65, v65, v66
	v_exp_f32_e32 v66, v65
	v_or_b32_e32 v65, 0xd9, v114
	v_sub_u32_e32 v65, v116, v65
	v_sub_u32_e32 v68, 0, v65
	v_max_i32_e32 v68, v65, v68
	v_cvt_f32_u32_e32 v68, v68
	v_cmp_gt_i32_e32 vcc, 0, v65
	s_nop 1
	v_cndmask_b32_e32 v65, v115, v117, vcc
	v_mul_f32_e32 v65, v65, v68
	v_sub_u32_e32 v68, 0, v67
	v_max_i32_e32 v68, v67, v68
	v_cvt_f32_u32_e32 v68, v68
	v_cmp_gt_i32_e32 vcc, 0, v67
	v_exp_f32_e32 v65, v65
	s_nop 0
	v_cndmask_b32_e32 v67, v115, v117, vcc
	v_mul_f32_e32 v67, v67, v68
	v_exp_f32_e32 v67, v67
	v_pk_mul_f32 v[64:65], v[64:65], s[2:3] op_sel_hi:[1,0]
	s_nop 0
	v_pk_mul_f32 v[60:61], v[64:65], v[60:61]
	v_pk_mul_f32 v[64:65], v[66:67], s[2:3] op_sel_hi:[1,0]
	v_or_b32_e32 v67, 0xfb, v114
	v_pk_mul_f32 v[44:45], v[64:65], v[44:45]
	v_or_b32_e32 v64, 0xda, v114
	v_sub_u32_e32 v64, v116, v64
	v_sub_u32_e32 v66, 0, v64
	v_max_i32_e32 v66, v64, v66
	v_cvt_f32_u32_e32 v66, v66
	v_or_b32_e32 v65, 0xfa, v114
	v_cmp_gt_i32_e32 vcc, 0, v64
	v_sub_u32_e32 v65, v116, v65
	v_sub_u32_e32 v67, v116, v67
	v_cndmask_b32_e32 v64, v115, v117, vcc
	v_mul_f32_e32 v64, v64, v66
	v_sub_u32_e32 v66, 0, v65
	v_max_i32_e32 v66, v65, v66
	v_cvt_f32_u32_e32 v66, v66
	v_cmp_gt_i32_e32 vcc, 0, v65
	v_exp_f32_e32 v64, v64
	s_nop 0
	v_cndmask_b32_e32 v65, v115, v117, vcc
	v_mul_f32_e32 v65, v65, v66
	v_exp_f32_e32 v66, v65
	v_or_b32_e32 v65, 0xdb, v114
	v_sub_u32_e32 v65, v116, v65
	v_sub_u32_e32 v68, 0, v65
	v_max_i32_e32 v68, v65, v68
	v_cvt_f32_u32_e32 v68, v68
	v_cmp_gt_i32_e32 vcc, 0, v65
	s_nop 1
	v_cndmask_b32_e32 v65, v115, v117, vcc
	v_mul_f32_e32 v65, v65, v68
	v_sub_u32_e32 v68, 0, v67
	v_max_i32_e32 v68, v67, v68
	v_cvt_f32_u32_e32 v68, v68
	v_cmp_gt_i32_e32 vcc, 0, v67
	v_exp_f32_e32 v65, v65
	s_nop 0
	v_cndmask_b32_e32 v67, v115, v117, vcc
	v_mul_f32_e32 v67, v67, v68
	v_exp_f32_e32 v67, v67
	v_pk_mul_f32 v[64:65], v[64:65], s[2:3] op_sel_hi:[1,0]
	s_nop 0
	v_pk_mul_f32 v[70:71], v[64:65], v[62:63]
	v_pk_mul_f32 v[62:63], v[66:67], s[2:3] op_sel_hi:[1,0]
	s_nop 0
	v_pk_mul_f32 v[46:47], v[62:63], v[46:47]
	ds_read_b128 v[52:55], v74 offset:32256
	ds_read_b128 v[62:65], v74 offset:27648
	ds_read_b128 v[66:69], v74 offset:27680
	s_waitcnt lgkmcnt(2)
	v_mfma_f32_32x32x16_bf16 v[16:31], v[52:55], v[48:51], v[16:31]
	ds_read_b128 v[52:55], v74 offset:32288
	s_waitcnt lgkmcnt(2)
	v_mfma_f32_32x32x16_bf16 v[0:15], v[62:65], v[48:51], v[0:15]
	v_cvt_pk_bf16_f32 v48, v56, v57
	v_cvt_pk_bf16_f32 v49, v58, v59
	v_cvt_pk_bf16_f32 v50, v60, v61
	v_cvt_pk_bf16_f32 v51, v70, v71
	s_waitcnt lgkmcnt(1)
	s_nop 0
	v_mfma_f32_32x32x16_bf16 v[0:15], v[66:69], v[48:51], v[0:15]
	s_waitcnt lgkmcnt(0)
	v_mfma_f32_32x32x16_bf16 v[16:31], v[52:55], v[48:51], v[16:31]
	ds_read_b128 v[36:39], v74 offset:27712
	ds_read_b128 v[48:51], v74 offset:32320
	s_waitcnt lgkmcnt(1)
	v_mfma_f32_32x32x16_bf16 v[0:15], v[36:39], v[32:35], v[0:15]
	s_waitcnt lgkmcnt(0)
	v_mfma_f32_32x32x16_bf16 v[16:31], v[48:51], v[32:35], v[16:31]
	v_cvt_pk_bf16_f32 v32, v40, v41
	v_cvt_pk_bf16_f32 v33, v42, v43
	ds_read_b128 v[36:39], v74 offset:27744
	ds_read_b128 v[40:43], v74 offset:32352
	v_cvt_pk_bf16_f32 v34, v44, v45
	v_cvt_pk_bf16_f32 v35, v46, v47
	s_waitcnt lgkmcnt(0)
	s_barrier
	v_mfma_f32_32x32x16_bf16 v[0:15], v[36:39], v[32:35], v[0:15]
	v_mfma_f32_32x32x16_bf16 v[16:31], v[40:43], v[32:35], v[16:31]
	s_cbranch_scc1 .LBB0_1187
	v_lshlrev_b32_e32 v130, 7, v73
	v_lshl_add_u64 v[32:33], s[4:5], 0, v[130:131]
	v_lshlrev_b32_e32 v130, 1, v72
	v_lshl_add_u64 v[126:127], v[32:33], 0, v[130:131]
	v_add_co_u32_e32 v146, vcc, 0x1000, v126
	global_load_dwordx4 v[32:35], v[126:127], off
	s_nop 0
	v_addc_co_u32_e32 v147, vcc, 0, v127, vcc
	v_add_co_u32_e32 v148, vcc, 0x2000, v126
	global_load_dwordx4 v[36:39], v[146:147], off
	s_nop 0
	v_addc_co_u32_e32 v149, vcc, 0, v127, vcc
	v_add_co_u32_e32 v150, vcc, 0x3000, v126
	global_load_dwordx4 v[48:51], v[148:149], off
	s_nop 0
	v_addc_co_u32_e32 v151, vcc, 0, v127, vcc
	global_load_dwordx4 v[52:55], v[150:151], off
	s_waitcnt vmcnt(3)
	v_mfma_f32_32x32x16_bf16 v[64:79], v[32:35], v[108:111], 0
	s_waitcnt vmcnt(2)
	v_mfma_f32_32x32x16_bf16 v[32:47], v[36:39], v[108:111], 0
	s_waitcnt vmcnt(1)
	v_mfma_f32_32x32x16_bf16 v[80:95], v[48:51], v[108:111], 0
	s_waitcnt vmcnt(0)
	v_mfma_f32_32x32x16_bf16 v[48:63], v[52:55], v[108:111], 0
	global_load_dwordx4 v[108:111], v[126:127], off offset:32
	global_load_dwordx4 v[118:121], v[146:147], off offset:32
	global_load_dwordx4 v[122:125], v[148:149], off offset:32
	global_load_dwordx4 v[142:145], v[150:151], off offset:32
	s_waitcnt vmcnt(3)
	v_mfma_f32_32x32x16_bf16 v[64:79], v[108:111], v[104:107], v[64:79]
	s_waitcnt vmcnt(2)
	v_mfma_f32_32x32x16_bf16 v[32:47], v[118:121], v[104:107], v[32:47]
	s_waitcnt vmcnt(1)
	v_mfma_f32_32x32x16_bf16 v[80:95], v[122:125], v[104:107], v[80:95]
	s_waitcnt vmcnt(0)
	v_mfma_f32_32x32x16_bf16 v[48:63], v[142:145], v[104:107], v[48:63]
	global_load_dwordx4 v[104:107], v[126:127], off offset:64
	global_load_dwordx4 v[108:111], v[146:147], off offset:64
	global_load_dwordx4 v[118:121], v[148:149], off offset:64
	global_load_dwordx4 v[122:125], v[150:151], off offset:64
	s_waitcnt vmcnt(3)
	v_mfma_f32_32x32x16_bf16 v[64:79], v[104:107], v[100:103], v[64:79]
	s_waitcnt vmcnt(2)
	v_mfma_f32_32x32x16_bf16 v[32:47], v[108:111], v[100:103], v[32:47]
	s_waitcnt vmcnt(1)
	v_mfma_f32_32x32x16_bf16 v[80:95], v[118:121], v[100:103], v[80:95]
	s_waitcnt vmcnt(0)
	v_mfma_f32_32x32x16_bf16 v[48:63], v[122:125], v[100:103], v[48:63]
	global_load_dwordx4 v[100:103], v[126:127], off offset:96
	global_load_dwordx4 v[104:107], v[146:147], off offset:96
	global_load_dwordx4 v[108:111], v[148:149], off offset:96
	global_load_dwordx4 v[118:121], v[150:151], off offset:96
	s_waitcnt vmcnt(3)
	v_mfma_f32_32x32x16_bf16 v[64:79], v[100:103], v[96:99], v[64:79]
	s_waitcnt vmcnt(2)
	v_mfma_f32_32x32x16_bf16 v[32:47], v[104:107], v[96:99], v[32:47]
	s_waitcnt vmcnt(1)
	v_mfma_f32_32x32x16_bf16 v[80:95], v[108:111], v[96:99], v[80:95]
	s_waitcnt vmcnt(0)
	v_mfma_f32_32x32x16_bf16 v[48:63], v[118:121], v[96:99], v[48:63]
	v_sub_u32_e32 v97, 0x100, v116
	v_add_u32_e32 v96, 1, v116
	v_cvt_f32_i32_e32 v97, v97
	v_cvt_f32_i32_e32 v96, v96
	v_mul_f32_e32 v97, v117, v97
	v_mul_f32_e32 v96, v115, v96
	v_exp_f32_e32 v98, v97
	v_exp_f32_e32 v96, v96
	s_nop 3
	v_pk_mul_f32 v[48:49], v[98:99], v[48:49] op_sel_hi:[0,1]
	v_pk_fma_f32 v[32:33], v[96:97], v[32:33], v[48:49] op_sel_hi:[0,1,1]
	v_pk_add_f32 v[16:17], v[16:17], v[32:33]
	v_pk_mul_f32 v[32:33], v[98:99], v[82:83] op_sel_hi:[0,1]
	v_pk_fma_f32 v[32:33], v[96:97], v[66:67], v[32:33] op_sel_hi:[0,1,1]
	v_pk_add_f32 v[2:3], v[2:3], v[32:33]
	v_pk_mul_f32 v[32:33], v[98:99], v[50:51] op_sel_hi:[0,1]
	v_pk_fma_f32 v[32:33], v[96:97], v[34:35], v[32:33] op_sel_hi:[0,1,1]
	v_pk_add_f32 v[18:19], v[18:19], v[32:33]
	v_pk_mul_f32 v[32:33], v[98:99], v[84:85] op_sel_hi:[0,1]
	v_pk_fma_f32 v[32:33], v[96:97], v[68:69], v[32:33] op_sel_hi:[0,1,1]
	v_pk_add_f32 v[4:5], v[4:5], v[32:33]
	v_pk_mul_f32 v[32:33], v[98:99], v[52:53] op_sel_hi:[0,1]
	v_pk_fma_f32 v[32:33], v[96:97], v[36:37], v[32:33] op_sel_hi:[0,1,1]
	v_pk_add_f32 v[20:21], v[20:21], v[32:33]
	v_pk_mul_f32 v[32:33], v[98:99], v[86:87] op_sel_hi:[0,1]
	v_pk_fma_f32 v[32:33], v[96:97], v[70:71], v[32:33] op_sel_hi:[0,1,1]
	v_pk_add_f32 v[6:7], v[6:7], v[32:33]
	v_pk_mul_f32 v[32:33], v[98:99], v[54:55] op_sel_hi:[0,1]
	v_pk_fma_f32 v[32:33], v[96:97], v[38:39], v[32:33] op_sel_hi:[0,1,1]
	v_pk_add_f32 v[22:23], v[22:23], v[32:33]
	v_pk_mul_f32 v[32:33], v[98:99], v[88:89] op_sel_hi:[0,1]
	v_pk_fma_f32 v[32:33], v[96:97], v[72:73], v[32:33] op_sel_hi:[0,1,1]
	v_pk_add_f32 v[8:9], v[8:9], v[32:33]
	v_pk_mul_f32 v[32:33], v[98:99], v[56:57] op_sel_hi:[0,1]
	v_pk_fma_f32 v[32:33], v[96:97], v[40:41], v[32:33] op_sel_hi:[0,1,1]
	v_pk_add_f32 v[24:25], v[24:25], v[32:33]
	v_pk_mul_f32 v[32:33], v[98:99], v[90:91] op_sel_hi:[0,1]
	v_pk_fma_f32 v[32:33], v[96:97], v[74:75], v[32:33] op_sel_hi:[0,1,1]
	v_pk_add_f32 v[10:11], v[10:11], v[32:33]
	v_pk_mul_f32 v[32:33], v[98:99], v[58:59] op_sel_hi:[0,1]
	v_pk_fma_f32 v[32:33], v[96:97], v[42:43], v[32:33] op_sel_hi:[0,1,1]
	v_pk_add_f32 v[26:27], v[26:27], v[32:33]
	v_pk_mul_f32 v[32:33], v[98:99], v[92:93] op_sel_hi:[0,1]
	v_pk_fma_f32 v[32:33], v[96:97], v[76:77], v[32:33] op_sel_hi:[0,1,1]
	v_pk_mul_f32 v[80:81], v[98:99], v[80:81] op_sel_hi:[0,1]
	v_pk_add_f32 v[12:13], v[12:13], v[32:33]
	v_pk_mul_f32 v[32:33], v[98:99], v[60:61] op_sel_hi:[0,1]
	v_pk_fma_f32 v[64:65], v[96:97], v[64:65], v[80:81] op_sel_hi:[0,1,1]
	v_pk_fma_f32 v[32:33], v[96:97], v[44:45], v[32:33] op_sel_hi:[0,1,1]
	v_mul_f32_e32 v34, v98, v94
	v_mov_b32_e32 v97, v98
	v_mov_b32_e32 v94, v79
	v_pk_mul_f32 v[40:41], v[96:97], v[94:95]
	v_pk_add_f32 v[28:29], v[28:29], v[32:33]
	v_mul_f32_e32 v32, v96, v78
	v_mov_b32_e32 v33, v40
	v_mov_b32_e32 v35, v41
	v_mul_f32_e32 v38, v98, v62
	v_pk_add_f32 v[32:33], v[32:33], v[34:35]
	v_mov_b32_e32 v62, v47
	v_pk_add_f32 v[14:15], v[14:15], v[32:33]
	v_pk_mul_f32 v[32:33], v[96:97], v[62:63]
	v_mul_f32_e32 v36, v96, v46
	v_mov_b32_e32 v37, v32
	v_mov_b32_e32 v39, v33
	v_pk_add_f32 v[32:33], v[36:37], v[38:39]
	v_pk_add_f32 v[0:1], v[0:1], v[64:65]
	v_pk_add_f32 v[30:31], v[30:31], v[32:33]
